# SSD S2 gating / ssq arithmetic in packed f32 ops (v_pk_fma/add/mul): 24 fewer VALU instructions per chunk per wave, same operations
# speedup vs baseline: 1.0118x; 1.0113x over previous
; #define LAS __attribute__((address_space(3)))
; __device__ __forceinline__ bf16_t f2bf(float f) { return (bf16_t)(pk2(f, 0.f) & 0xffffu); }
; __device__ __forceinline__ float bflo(unsigned w) { return __uint_as_float(w << 16); }
; __device__ __forceinline__ float bfhi(unsigned w) { return __uint_as_float(w & 0xffff0000u); }
; __device__ __forceinline__ float siluf_(float x) { return x * __builtin_amdgcn_rcpf(1.f + __expf(-x)); }
; __device__ __forceinline__ void ssd_item(const Args& a, LAS unsigned char* lds, int layer, bool is_sample, int b, int h, int seq_row0, int nchunks,
;                                          bf16_t* proj, float* ssq, const int tid) {
;     ...
;         {
;             float o[8];
; #pragma unroll
;             for (int i = 0; i < 8; ++i) o[i] = cb[i];
; #pragma unroll
;             for (int k = 0; k < 4; ++k) { const u32x4 w = *(const LAS u32x4*)(lds + L_XRAW + (lane + k) * P64 + wave * 16);
;                 o[0] += cw[k][0] * bflo(w.x); o[1] += cw[k][1] * bfhi(w.x); o[2] += cw[k][2] * bflo(w.y); o[3] += cw[k][3] * bfhi(w.y);
;                 o[4] += cw[k][4] * bflo(w.z); o[5] += cw[k][5] * bfhi(w.z); o[6] += cw[k][6] * bflo(w.w); o[7] += cw[k][7] * bfhi(w.w); }
; #pragma unroll
;             for (int i = 0; i < 8; ++i) *(LAS bf16_t*)(lds + L_XST + (wave * 8 + i) * P64 + lane * 2) = f2bf(siluf_(o[i]));
;         }
;         {
;             const int oc = tid & 15, tk = (tid >> 4) * 2;
;             const float a63s = acv[63]; const float wa = dtv[tk] * __builtin_amdgcn_exp2f(a63s - acv[tk]), wb = dtv[tk + 1] * __builtin_amdgcn_exp2f(a63s - acv[tk + 1]);
.LBB0_570:
	ds_read_b128 v[148:151], v123
	ds_read_b128 v[152:155], v123 offset:144
	s_add_i32 s65, s15, 0
	s_add_i32 s65, s65, 0x1c73c
	v_add_u32_e32 v164, v110, v192
	s_waitcnt lgkmcnt(1)
	v_lshlrev_b32_e32 v102, 16, v148
	v_and_b32_e32 v103, 0xffff0000, v148
	v_lshlrev_b32_e32 v148, 16, v149
	v_fma_f32 v156, v8, v148, v40
	v_and_b32_e32 v148, 0xffff0000, v149
	v_fma_f32 v157, v9, v148, v41
	v_lshlrev_b32_e32 v148, 16, v150
	v_fma_f32 v158, v2, v148, v34
	v_and_b32_e32 v148, 0xffff0000, v150
	v_fma_f32 v159, v3, v148, v35
	v_lshlrev_b32_e32 v148, 16, v151
	v_fma_f32 v160, v4, v148, v36
	v_and_b32_e32 v148, 0xffff0000, v151
	v_fma_f32 v102, v6, v102, v38
	v_fma_f32 v161, v5, v148, v37
	s_waitcnt lgkmcnt(0)
	v_lshlrev_b32_e32 v148, 16, v152
	v_fma_f32 v103, v7, v103, v39
	v_fmac_f32_e32 v102, v10, v148
	v_and_b32_e32 v148, 0xffff0000, v152
	v_fmac_f32_e32 v103, v11, v148
	v_lshlrev_b32_e32 v148, 16, v153
	v_fmac_f32_e32 v156, v12, v148
	v_and_b32_e32 v148, 0xffff0000, v153
	v_fmac_f32_e32 v157, v13, v148
	v_lshlrev_b32_e32 v148, 16, v154
	v_fmac_f32_e32 v158, v14, v148
	v_and_b32_e32 v148, 0xffff0000, v154
	v_fmac_f32_e32 v159, v15, v148
	ds_read_b128 v[148:151], v123 offset:288
	v_lshlrev_b32_e32 v152, 16, v155
	v_fmac_f32_e32 v160, v16, v152
	v_and_b32_e32 v152, 0xffff0000, v155
	v_fmac_f32_e32 v161, v17, v152
	ds_read_b128 v[152:155], v123 offset:432
	s_waitcnt lgkmcnt(1)
	v_lshlrev_b32_e32 v162, 16, v148
	v_and_b32_e32 v148, 0xffff0000, v148
	v_fmac_f32_e32 v103, v19, v148
	v_lshlrev_b32_e32 v148, 16, v149
	v_fmac_f32_e32 v156, v20, v148
	v_and_b32_e32 v148, 0xffff0000, v149
	v_fmac_f32_e32 v157, v21, v148
	v_lshlrev_b32_e32 v148, 16, v150
	v_fmac_f32_e32 v158, v22, v148
	v_and_b32_e32 v148, 0xffff0000, v150
	v_fmac_f32_e32 v159, v23, v148
	v_lshlrev_b32_e32 v148, 16, v151
	v_fmac_f32_e32 v160, v24, v148
	v_and_b32_e32 v148, 0xffff0000, v151
	v_fmac_f32_e32 v102, v18, v162
	v_fmac_f32_e32 v161, v25, v148
	s_waitcnt lgkmcnt(0)
	v_lshlrev_b32_e32 v148, 16, v152
	v_fmac_f32_e32 v102, v26, v148
	v_and_b32_e32 v148, 0xffff0000, v152
	v_fmac_f32_e32 v103, v27, v148
	v_lshlrev_b32_e32 v148, 16, v153
	v_fmac_f32_e32 v156, v28, v148
	v_and_b32_e32 v148, 0xffff0000, v153
	v_fmac_f32_e32 v157, v29, v148
	v_lshlrev_b32_e32 v148, 16, v154
	v_fmac_f32_e32 v158, v30, v148
	v_and_b32_e32 v148, 0xffff0000, v154
	v_fmac_f32_e32 v159, v31, v148
	v_mul_f32_e32 v148, 0xbfb8aa3b, v102
	v_exp_f32_e32 v148, v148
	v_mul_f32_e32 v150, 0xbfb8aa3b, v103
	v_exp_f32_e32 v150, v150
	v_lshlrev_b32_e32 v149, 16, v155
	v_add_f32_e32 v148, 1.0, v148
	v_rcp_f32_e32 v148, v148
	v_fmac_f32_e32 v160, v32, v149
	v_and_b32_e32 v149, 0xffff0000, v155
	v_fmac_f32_e32 v161, v33, v149
	v_mul_f32_e32 v102, v102, v148
	v_add_f32_e32 v148, 1.0, v150
	v_mul_f32_e32 v149, 0xbfb8aa3b, v156
	v_rcp_f32_e32 v148, v148
	v_exp_f32_e32 v149, v149
	v_cvt_pk_bf16_f32 v102, v102, v1
	ds_write_b16 v124, v102
	v_mul_f32_e32 v102, v103, v148
	v_add_f32_e32 v103, 1.0, v149
	v_mul_f32_e32 v148, 0xbfb8aa3b, v157
	v_rcp_f32_e32 v103, v103
	v_exp_f32_e32 v148, v148
	v_cvt_pk_bf16_f32 v102, v102, v1
	ds_write_b16 v124, v102 offset:144
	v_mul_f32_e32 v102, v156, v103
	v_add_f32_e32 v103, 1.0, v148
	v_mul_f32_e32 v148, 0xbfb8aa3b, v158
	v_rcp_f32_e32 v103, v103
	v_exp_f32_e32 v148, v148
	v_cvt_pk_bf16_f32 v102, v102, v1
	ds_write_b16 v124, v102 offset:288
	v_mul_f32_e32 v102, v157, v103
	v_add_f32_e32 v103, 1.0, v148
	v_mul_f32_e32 v148, 0xbfb8aa3b, v159
	v_rcp_f32_e32 v103, v103
	v_exp_f32_e32 v148, v148
	v_cvt_pk_bf16_f32 v102, v102, v1
	ds_write_b16 v124, v102 offset:432
	v_mul_f32_e32 v102, v158, v103
	v_add_f32_e32 v103, 1.0, v148
	v_mul_f32_e32 v148, 0xbfb8aa3b, v160
	v_rcp_f32_e32 v103, v103
	v_exp_f32_e32 v148, v148
	v_cvt_pk_bf16_f32 v102, v102, v1
	ds_write_b16 v194, v102 offset:576
	v_mul_f32_e32 v102, v159, v103
	v_add_f32_e32 v103, 1.0, v148
	v_mul_f32_e32 v148, 0xbfb8aa3b, v161
	v_rcp_f32_e32 v103, v103
	v_exp_f32_e32 v148, v148
	v_cvt_pk_bf16_f32 v102, v102, v1
	v_add_u32_e32 v149, s15, v120
	v_add_u32_e32 v151, s15, v119
	ds_write_b16 v194, v102 offset:720
	v_mul_f32_e32 v102, v160, v103
	v_add_f32_e32 v103, 1.0, v148
	v_mov_b32_e32 v148, s65
	v_add_u32_e32 v150, 0x1a640, v149
	v_add_u32_e32 v149, 0x1c640, v149
	v_add_u32_e32 v152, 0x1a640, v151
	v_add_u32_e32 v151, 0x1c640, v151
	ds_read_b32 v148, v148
	ds_read_b32 v150, v150
	ds_read_b32 v149, v149
	ds_read_b32 v152, v152
	ds_read_b32 v151, v151
	v_rcp_f32_e32 v103, v103
	v_cvt_pk_bf16_f32 v102, v102, v1
	ds_write_b16 v194, v102 offset:864
	v_add_u32_e32 v165, s15, v117
	v_mul_f32_e32 v102, v161, v103
	s_waitcnt lgkmcnt(3)
	v_sub_f32_e32 v103, v148, v149
	s_waitcnt lgkmcnt(1)
; #define LAS __attribute__((address_space(3)))
; __device__ __forceinline__ float bflo(unsigned w) { return __uint_as_float(w << 16); }
; __device__ __forceinline__ void ssd_item(const Args& a, LAS unsigned char* lds, int layer, bool is_sample, int b, int h, int seq_row0, int nchunks,
;                                          bf16_t* proj, float* ssq, const int tid) {
;     ...
;         {
;             const int oc = tid & 15, tk = (tid >> 4) * 2;
;             const float a63s = acv[63]; const float wa = dtv[tk] * __builtin_amdgcn_exp2f(a63s - acv[tk]), wb = dtv[tk + 1] * __builtin_amdgcn_exp2f(a63s - acv[tk + 1]);
;             LAS unsigned char* d = lds + L_BWT + (oc * 8) * P64 + ((((tk >> 3) ^ ((oc >> 1) & 7)) << 4) | ((tk * 2) & 15));
;             *(LAS unsigned*)(d + 0 * P64) = pk2(bflo(bo0.x) * wa, bflo(bo1.x) * wb); *(LAS unsigned*)(d + 1 * P64) = pk2(bfhi(bo0.x) * wa, bfhi(bo1.x) * wb);
;             *(LAS unsigned*)(d + 2 * P64) = pk2(bflo(bo0.y) * wa, bflo(bo1.y) * wb); *(LAS unsigned*)(d + 3 * P64) = pk2(bfhi(bo0.y) * wa, bfhi(bo1.y) * wb);
;             *(LAS unsigned*)(d + 4 * P64) = pk2(bflo(bo0.z) * wa, bflo(bo1.z) * wb); *(LAS unsigned*)(d + 5 * P64) = pk2(bfhi(bo0.z) * wa, bfhi(bo1.z) * wb);
;             *(LAS unsigned*)(d + 6 * P64) = pk2(bflo(bo0.w) * wa, bflo(bo1.w) * wb); *(LAS unsigned*)(d + 7 * P64) = pk2(bfhi(bo0.w) * wa, bfhi(bo1.w) * wb);
;         }
;         {
;             float al[4];
; #pragma unroll
;             for (int j = 0; j < 4; ++j) al[j] = acv[16 * rb + 4 * fq + j];
; #pragma unroll
;             for (int ci = 0; ci < 2; ++ci) { const int cbk = (wave & 1) * 2 + ci; f32x4 acc = (f32x4){0.f, 0.f, 0.f, 0.f};
; #pragma unroll
;                 for (int ks = 0; ks < 4; ++ks) { const bf16x8 av = *(const LAS bf16x8*)(lds + L_CM + (16 * rb + fr) * P128 + (32 * ks + 8 * fq) * 2);
;                     const bf16x8 bv = *(const LAS bf16x8*)(lds + L_BM + (16 * cbk + fr) * P128 + (32 * ks + 8 * fq) * 2); acc = mfma16(av, bv, acc); }
;                 const int s = 16 * cbk + fr; const float as = acv[s], ds = dtv[s];
; #pragma unroll
;                 for (int j = 0; j < 4; ++j) { const int l = 16 * rb + 4 * fq + j;
;                     const float gv = (s <= l) ? acc[j] * __builtin_amdgcn_exp2f(al[j] - as) * ds : 0.f;
;                     *(LAS bf16_t*)(lds + L_G + l * P64 + s * 2) = f2bf(gv); } }
;         }
;         LBAR();
	v_sub_f32_e32 v148, v148, v151
	v_exp_f32_e32 v103, v103
	v_exp_f32_e32 v148, v148
	v_cvt_pk_bf16_f32 v102, v102, v1
	ds_write_b16 v194, v102 offset:1008
	v_mul_f32_e32 v102, v150, v103
	v_mul_f32_e32 v103, v152, v148
	v_lshlrev_b32_e32 v148, 16, v58
	v_lshlrev_b32_e32 v149, 16, v62
	v_and_b32_e32 v58, 0xffff0000, v58
	v_and_b32_e32 v62, 0xffff0000, v62
	v_mul_f32_e32 v58, v102, v58
	v_mul_f32_e32 v62, v103, v62
	v_mul_f32_e32 v148, v102, v148
	v_cvt_pk_bf16_f32 v58, v58, v62
	v_add_u32_e32 v62, 0xd000, v125
	v_mul_f32_e32 v149, v103, v149
	v_cvt_pk_bf16_f32 v148, v148, v149
	ds_write2_b32 v62, v148, v58 offset1:36
	v_lshlrev_b32_e32 v58, 16, v59
	v_and_b32_e32 v59, 0xffff0000, v59
	v_mul_f32_e32 v58, v102, v58
	v_lshlrev_b32_e32 v148, 16, v63
	v_mul_f32_e32 v59, v102, v59
	v_and_b32_e32 v63, 0xffff0000, v63
	v_mul_f32_e32 v148, v103, v148
	v_cvt_pk_bf16_f32 v58, v58, v148
	v_mul_f32_e32 v63, v103, v63
	v_cvt_pk_bf16_f32 v59, v59, v63
	ds_write2_b32 v62, v58, v59 offset0:72 offset1:108
	v_lshlrev_b32_e32 v58, 16, v60
	v_lshlrev_b32_e32 v59, 16, v64
	v_mul_f32_e32 v58, v102, v58
	v_mul_f32_e32 v59, v103, v59
	v_cvt_pk_bf16_f32 v58, v58, v59
	v_and_b32_e32 v59, 0xffff0000, v60
	v_mul_f32_e32 v59, v102, v59
	v_and_b32_e32 v60, 0xffff0000, v64
	v_mul_f32_e32 v60, v103, v60
	v_cvt_pk_bf16_f32 v59, v59, v60
	ds_write2_b32 v62, v58, v59 offset0:144 offset1:180
	v_lshlrev_b32_e32 v58, 16, v61
	v_lshlrev_b32_e32 v59, 16, v65
	v_mul_f32_e32 v58, v102, v58
	v_mul_f32_e32 v59, v103, v59
	v_cvt_pk_bf16_f32 v58, v58, v59
	v_and_b32_e32 v59, 0xffff0000, v61
	v_mul_f32_e32 v59, v102, v59
	v_and_b32_e32 v60, 0xffff0000, v65
	v_mul_f32_e32 v60, v103, v60
	v_cvt_pk_bf16_f32 v59, v59, v60
	ds_write2_b32 v62, v58, v59 offset0:216 offset1:252
	ds_read_b128 v[58:61], v164 offset:18432
	v_add_u32_e32 v102, v111, v192
	ds_read_b128 v[62:65], v102 offset:35840
	ds_read_b128 v[148:151], v164 offset:18496
	ds_read_b128 v[152:155], v164 offset:18624
	s_waitcnt lgkmcnt(2)
	v_mfma_f32_16x16x32_bf16 v[58:61], v[58:61], v[62:65], 0
	ds_read_b128 v[62:65], v164 offset:18560
	ds_read_b128 v[156:159], v102 offset:35904
	ds_read_b128 v[160:163], v102 offset:35968
	v_add_u32_e32 v103, s15, v118
	v_add_u32_e32 v103, 0x1c640, v103
	s_waitcnt lgkmcnt(1)
	v_mfma_f32_16x16x32_bf16 v[58:61], v[148:151], v[156:159], v[58:61]
	ds_read_b128 v[148:151], v103
	v_add_u32_e32 v157, 0x1a640, v165
	v_add_u32_e32 v158, 0x1c680, v165
	s_waitcnt lgkmcnt(1)
	v_mfma_f32_16x16x32_bf16 v[58:61], v[62:65], v[160:163], v[58:61]
	v_add_u32_e32 v62, 0x1c640, v165
	ds_read_b32 v156, v62
	ds_read_b128 v[62:65], v102 offset:36032
	ds_read_b32 v102, v157
	ds_read_b32 v169, v158
	s_waitcnt lgkmcnt(2)
	v_mfma_f32_16x16x32_bf16 v[58:61], v[152:155], v[62:65], v[58:61]
	v_sub_f32_e32 v157, v148, v156
	v_exp_f32_e32 v157, v157
	v_sub_f32_e32 v62, v149, v156
	v_exp_f32_e32 v62, v62
	v_add_u32_e32 v63, v112, v195
	s_nop 2
	v_mul_f32_e32 v58, v58, v157
	s_waitcnt lgkmcnt(1)
	v_mul_f32_e32 v58, v102, v58
	v_cndmask_b32_e64 v58, v58, 0, s[40:41]
	v_cvt_pk_bf16_f32 v58, v58, v1
	ds_write_b16 v63, v58 offset:9216
	v_mul_f32_e32 v58, v59, v62
	v_sub_f32_e32 v59, v150, v156
	v_exp_f32_e32 v59, v59
	v_mul_f32_e32 v58, v102, v58
	v_cndmask_b32_e64 v58, v58, 0, s[42:43]
	v_cvt_pk_bf16_f32 v58, v58, v1
	ds_write_b16 v63, v58 offset:9360
	v_mul_f32_e32 v58, v60, v59
	v_sub_f32_e32 v59, v151, v156
	v_exp_f32_e32 v59, v59
	v_mul_f32_e32 v58, v102, v58
	v_cndmask_b32_e64 v58, v58, 0, s[44:45]
	v_cvt_pk_bf16_f32 v58, v58, v1
	ds_write_b16 v63, v58 offset:9504
	v_mul_f32_e32 v58, v61, v59
	v_mul_f32_e32 v58, v102, v58
	v_cndmask_b32_e64 v58, v58, 0, s[46:47]
	v_cvt_pk_bf16_f32 v58, v58, v1
	ds_write_b16 v63, v58 offset:9648
	ds_read_b128 v[58:61], v164 offset:18432
	v_add_u32_e32 v102, v114, v192
	ds_read_b128 v[62:65], v164 offset:18496
	ds_read_b128 v[152:155], v102 offset:35840
	ds_read_b128 v[156:159], v102 offset:35904
	s_waitcnt lgkmcnt(1)
	v_mfma_f32_16x16x32_bf16 v[58:61], v[58:61], v[152:155], 0
	ds_read_b128 v[152:155], v164 offset:18560
	s_waitcnt lgkmcnt(1)
	v_mfma_f32_16x16x32_bf16 v[58:61], v[62:65], v[156:159], v[58:61]
	ds_read_b128 v[62:65], v102 offset:35968
	ds_read_b128 v[156:159], v164 offset:18624
	ds_read_b128 v[160:163], v102 offset:36032
	s_waitcnt lgkmcnt(2)
	v_mfma_f32_16x16x32_bf16 v[58:61], v[152:155], v[62:65], v[58:61]
	v_sub_f32_e32 v63, v148, v169
	v_add_u32_e32 v62, 0x1a680, v165
	v_exp_f32_e32 v63, v63
	s_waitcnt lgkmcnt(0)
	v_mfma_f32_16x16x32_bf16 v[58:61], v[156:159], v[160:163], v[58:61]
	ds_read_b32 v62, v62
	v_add_u32_e32 v64, v115, v195
	s_nop 5
	v_mul_f32_e32 v58, v58, v63
	v_sub_f32_e32 v63, v149, v169
	v_exp_f32_e32 v63, v63
	s_waitcnt lgkmcnt(0)
	v_mul_f32_e32 v58, v62, v58
	v_cndmask_b32_e64 v58, v58, 0, s[48:49]
	v_cvt_pk_bf16_f32 v58, v58, v1
	ds_write_b16 v64, v58 offset:9216
	v_mul_f32_e32 v58, v59, v63
	v_sub_f32_e32 v59, v150, v169
	v_exp_f32_e32 v59, v59
	v_mul_f32_e32 v58, v62, v58
	v_cndmask_b32_e64 v58, v58, 0, s[50:51]
	v_cvt_pk_bf16_f32 v58, v58, v1
	ds_write_b16 v64, v58 offset:9360
	v_mul_f32_e32 v58, v60, v59
	v_sub_f32_e32 v59, v151, v169
	v_exp_f32_e32 v59, v59
	v_mul_f32_e32 v58, v62, v58
	v_cndmask_b32_e64 v58, v58, 0, s[52:53]
	v_cvt_pk_bf16_f32 v58, v58, v1
	ds_write_b16 v64, v58 offset:9504
	v_mul_f32_e32 v58, v61, v59
	v_mul_f32_e32 v58, v62, v58
	v_cndmask_b32_e64 v58, v58, 0, s[54:55]
	v_cvt_pk_bf16_f32 v58, v58, v1
	ds_write_b16 v64, v58 offset:9648
	s_waitcnt lgkmcnt(0)
	s_barrier
; __device__ __forceinline__ void ssd_item(const Args& a, LAS unsigned char* lds, int layer, bool is_sample, int b, int h, int seq_row0, int nchunks,
;                                          bf16_t* proj, float* ssq, const int tid) {
;     ...
;             float sq[4] = {0.f, 0.f, 0.f, 0.f}, el[4];
; #pragma unroll
;             for (int j = 0; j < 4; ++j) el[j] = __builtin_amdgcn_exp2f(acv[16 * rb + 4 * fq + j]);
; #pragma unroll
;             for (int ci = 0; ci < 2; ++ci) { const int cbk = (wave & 1) * 2 + ci; f32x4 acc = (f32x4){0.f, 0.f, 0.f, 0.f}, acp = (f32x4){0.f, 0.f, 0.f, 0.f};
; #pragma unroll
;                 for (int ks = 0; ks < 2; ++ks) { const bf16x8 av = *(const LAS bf16x8*)(lds + L_G + (16 * rb + fr) * P64 + (32 * ks + 8 * fq) * 2);
;                     const bf16x8 bv = *(const LAS bf16x8*)(lds + L_XST + (16 * cbk + fr) * P64 + (32 * ks + 8 * fq) * 2); acc = mfma16(av, bv, acc); }
; #pragma unroll
;                 for (int ks = 0; ks < 4; ++ks) { const bf16x8 av = *(const LAS bf16x8*)(lds + L_CM + (16 * rb + fr) * P128 + (32 * ks + 8 * fq) * 2);
;                     const bf16x8 bv = *(const LAS bf16x8*)(lds + L_ST + (16 * cbk + fr) * P128 + (32 * ks + 8 * fq) * 2); acp = mfma16(av, bv, acp); }
;                 const int p = 16 * cbk + fr;
;                 const u32x2 xs4 = *(const LAS u32x2*)(lds + L_XST + p * P64 + (16 * rb + 4 * fq) * 2);
;                 const float xsv[4] = {bflo(xs4.x), bfhi(xs4.x), bflo(xs4.y), bfhi(xs4.y)};
; #pragma unroll
;                 for (int j = 0; j < 4; ++j) { const int l = 16 * rb + 4 * fq + j;
;                     LAS bf16_t* zp = (LAS bf16_t*)(lds + L_ZT + l * P64 + p * 2);
;                     const float z = bf2f(*zp);
;                     const float yg = (acc[j] + el[j] * acp[j] + xsv[j] * dsk) * siluf_(z);
;                     *zp = f2bf(yg); sq[j] += yg * yg; } }
; #pragma unroll
;             for (int j = 0; j < 4; ++j) { const float v = row16_sum(sq[j]);
;                 if (fr == 0) ssqp[(16 * rb + 4 * fq + j) * 2 + (wave & 1)] = v; }
;             const float dec = __builtin_amdgcn_exp2f(acv[63]);
; #pragma unroll
;             for (int i = 0; i < 4; ++i) { st[i] = st[i] * dec;
; #pragma unroll
;                 for (int ks = 0; ks < 2; ++ks) { const bf16x8 av = *(const LAS bf16x8*)(lds + L_XST + (16 * pb + fr) * P64 + (32 * ks + 8 * fq) * 2);
	v_mov_b32_e32 v58, s65
	ds_read_b32 v102, v58
	ds_read_b128 v[148:151], v147
	ds_read_b128 v[176:179], v137 offset:53248
	ds_read_b128 v[180:183], v139 offset:53248
	ds_read_b128 v[184:187], v141 offset:53248
	ds_read_b128 v[188:191], v143 offset:53248
	ds_read_b128 v[152:155], v147 offset:64
	ds_read_b128 v[216:219], v138 offset:53248
	ds_read_b128 v[220:223], v140 offset:53248
	ds_read_b128 v[224:227], v142 offset:53248
	ds_read_b128 v[228:231], v144 offset:53248
	ds_read_b128 v[156:159], v147 offset:9216
	ds_read_b128 v[160:163], v147 offset:9280
	s_waitcnt lgkmcnt(12)
	v_exp_f32_e32 v102, v102
	s_nop 0
	v_pk_mul_f32 v[66:67], v[66:67], v[102:103] op_sel_hi:[1,0]
	v_pk_mul_f32 v[68:69], v[68:69], v[102:103] op_sel_hi:[1,0]
	v_pk_mul_f32 v[78:79], v[78:79], v[102:103] op_sel_hi:[1,0]
	v_pk_mul_f32 v[80:81], v[80:81], v[102:103] op_sel_hi:[1,0]
	v_pk_mul_f32 v[70:71], v[70:71], v[102:103] op_sel_hi:[1,0]
	v_pk_mul_f32 v[72:73], v[72:73], v[102:103] op_sel_hi:[1,0]
	v_pk_mul_f32 v[74:75], v[74:75], v[102:103] op_sel_hi:[1,0]
	v_pk_mul_f32 v[76:77], v[76:77], v[102:103] op_sel_hi:[1,0]
	s_waitcnt lgkmcnt(11)
	s_waitcnt lgkmcnt(10)
	v_mfma_f32_16x16x32_bf16 v[66:69], v[176:179], v[148:151], v[66:69]
	s_waitcnt lgkmcnt(9)
	v_mfma_f32_16x16x32_bf16 v[78:81], v[180:183], v[148:151], v[78:81]
	s_waitcnt lgkmcnt(8)
	v_mfma_f32_16x16x32_bf16 v[70:73], v[184:187], v[148:151], v[70:73]
	s_waitcnt lgkmcnt(7)
	v_mfma_f32_16x16x32_bf16 v[74:77], v[188:191], v[148:151], v[74:77]
	ds_read_b128 v[232:235], v164 offset:18432
	ds_read_b128 v[236:239], v164 offset:18496
	ds_read_b128 v[240:243], v164 offset:18560
	ds_read_b128 v[244:247], v164 offset:18624
	ds_read_b128 v[176:179], v127
	ds_read_b128 v[180:183], v127 offset:64
	ds_read_b128 v[184:187], v127 offset:128
	ds_read_b128 v[188:191], v127 offset:192
	s_waitcnt lgkmcnt(14)
	s_waitcnt lgkmcnt(13)
	v_mfma_f32_16x16x32_bf16 v[66:69], v[216:219], v[152:155], v[66:69]
	s_waitcnt lgkmcnt(12)
	v_mfma_f32_16x16x32_bf16 v[78:81], v[220:223], v[152:155], v[78:81]
	s_waitcnt lgkmcnt(11)
	v_mfma_f32_16x16x32_bf16 v[70:73], v[224:227], v[152:155], v[70:73]
	s_waitcnt lgkmcnt(10)
	v_mfma_f32_16x16x32_bf16 v[74:77], v[228:231], v[152:155], v[74:77]
	ds_read_b128 v[148:151], v126
	ds_read_b128 v[152:155], v126 offset:64
	ds_read_b64 v[248:249], v128
	ds_read_b64 v[250:251], v128 offset:2304
	s_waitcnt lgkmcnt(7)
	v_mfma_f32_16x16x32_bf16 v[176:179], v[232:235], v[176:179], 0
	ds_read_b128 v[216:219], v131
	ds_read_b128 v[220:223], v131 offset:64
	ds_read_b128 v[224:227], v131 offset:128
	ds_read_b128 v[228:231], v131 offset:192
	ds_read_b128 v[58:61], v130
	ds_read_b128 v[62:65], v130 offset:64
	s_waitcnt lgkmcnt(12)
	v_mfma_f32_16x16x32_bf16 v[176:179], v[236:239], v[180:183], v[176:179]
	s_waitcnt lgkmcnt(11)
	v_mfma_f32_16x16x32_bf16 v[176:179], v[240:243], v[184:187], v[176:179]
	s_waitcnt lgkmcnt(10)
	v_mfma_f32_16x16x32_bf16 v[176:179], v[244:247], v[188:191], v[176:179]
	s_waitcnt lgkmcnt(9)
	v_mfma_f32_16x16x32_bf16 v[148:151], v[156:159], v[148:151], 0
	ds_read_u16 v165, v129
	ds_read_u16 v169, v129 offset:144
	ds_read_u16 v170, v129 offset:288
	ds_read_u16 v171, v129 offset:432
	s_waitcnt lgkmcnt(12)
	v_mfma_f32_16x16x32_bf16 v[148:151], v[160:163], v[152:155], v[148:151]
	s_waitcnt lgkmcnt(9)
	v_mfma_f32_16x16x32_bf16 v[216:219], v[232:235], v[216:219], 0
	ds_read_b128 v[232:235], v103
	ds_read_u16 v172, v132
	ds_read_u16 v173, v132 offset:144
	ds_read_u16 v215, v132 offset:288
	ds_read_u16 v102, v132 offset:432
	s_waitcnt lgkmcnt(13)
	v_mfma_f32_16x16x32_bf16 v[216:219], v[236:239], v[220:223], v[216:219]
	s_waitcnt lgkmcnt(10)
	v_mfma_f32_16x16x32_bf16 v[58:61], v[156:159], v[58:61], 0
	s_waitcnt lgkmcnt(9)
	v_mfma_f32_16x16x32_bf16 v[58:61], v[160:163], v[62:65], v[58:61]
	s_waitcnt lgkmcnt(4)
; __device__ __forceinline__ void ssd_item(const Args& a, LAS unsigned char* lds, int layer, bool is_sample, int b, int h, int seq_row0, int nchunks,
;                                          bf16_t* proj, float* ssq, const int tid) {
;     ...
;             float sq[4] = {0.f, 0.f, 0.f, 0.f}, el[4];
; #pragma unroll
;             for (int j = 0; j < 4; ++j) el[j] = __builtin_amdgcn_exp2f(acv[16 * rb + 4 * fq + j]);
; #pragma unroll
;             for (int ci = 0; ci < 2; ++ci) { const int cbk = (wave & 1) * 2 + ci; f32x4 acc = (f32x4){0.f, 0.f, 0.f, 0.f}, acp = (f32x4){0.f, 0.f, 0.f, 0.f};
; #pragma unroll
;                 for (int ks = 0; ks < 2; ++ks) { const bf16x8 av = *(const LAS bf16x8*)(lds + L_G + (16 * rb + fr) * P64 + (32 * ks + 8 * fq) * 2);
;                     const bf16x8 bv = *(const LAS bf16x8*)(lds + L_XST + (16 * cbk + fr) * P64 + (32 * ks + 8 * fq) * 2); acc = mfma16(av, bv, acc); }
; #pragma unroll
;                 for (int ks = 0; ks < 4; ++ks) { const bf16x8 av = *(const LAS bf16x8*)(lds + L_CM + (16 * rb + fr) * P128 + (32 * ks + 8 * fq) * 2);
;                     const bf16x8 bv = *(const LAS bf16x8*)(lds + L_ST + (16 * cbk + fr) * P128 + (32 * ks + 8 * fq) * 2); acp = mfma16(av, bv, acp); }
;                 const int p = 16 * cbk + fr;
;                 const u32x2 xs4 = *(const LAS u32x2*)(lds + L_XST + p * P64 + (16 * rb + 4 * fq) * 2);
;                 const float xsv[4] = {bflo(xs4.x), bfhi(xs4.x), bflo(xs4.y), bfhi(xs4.y)};
; #pragma unroll
;                 for (int j = 0; j < 4; ++j) { const int l = 16 * rb + 4 * fq + j;
;                     LAS bf16_t* zp = (LAS bf16_t*)(lds + L_ZT + l * P64 + p * 2);
;                     const float z = bf2f(*zp);
;                     const float yg = (acc[j] + el[j] * acp[j] + xsv[j] * dsk) * siluf_(z);
;                     *zp = f2bf(yg); sq[j] += yg * yg; } }
; #pragma unroll
;             for (int j = 0; j < 4; ++j) { const float v = row16_sum(sq[j]);
;                 if (fr == 0) ssqp[(16 * rb + 4 * fq + j) * 2 + (wave & 1)] = v; }
;             const float dec = __builtin_amdgcn_exp2f(acv[63]);
; #pragma unroll
;             for (int i = 0; i < 4; ++i) { st[i] = st[i] * dec;
; #pragma unroll
;                 for (int ks = 0; ks < 2; ++ks) { const bf16x8 av = *(const LAS bf16x8*)(lds + L_XST + (16 * pb + fr) * P64 + (32 * ks + 8 * fq) * 2);
	v_exp_f32_e32 v232, v232
	v_exp_f32_e32 v233, v233
	v_exp_f32_e32 v234, v234
	v_exp_f32_e32 v235, v235
	v_mfma_f32_16x16x32_bf16 v[216:219], v[240:243], v[224:227], v[216:219]
	v_lshlrev_b32_e32 v180, 16, v248
	v_and_b32_e32 v181, 0xffff0000, v248
	v_lshlrev_b32_e32 v182, 16, v249
	v_and_b32_e32 v183, 0xffff0000, v249
	v_mfma_f32_16x16x32_bf16 v[216:219], v[244:247], v[228:231], v[216:219]
	v_lshlrev_b32_e32 v184, 16, v165
	v_lshlrev_b32_e32 v185, 16, v169
	v_lshlrev_b32_e32 v186, 16, v170
	v_lshlrev_b32_e32 v187, 16, v171
	v_mul_f32_e32 v188, 0xbfb8aa3b, v184
	v_mul_f32_e32 v189, 0xbfb8aa3b, v185
	v_mul_f32_e32 v190, 0xbfb8aa3b, v186
	v_mul_f32_e32 v191, 0xbfb8aa3b, v187
	v_exp_f32_e32 v188, v188
	v_exp_f32_e32 v189, v189
	v_exp_f32_e32 v190, v190
	v_exp_f32_e32 v191, v191
	v_pk_fma_f32 v[148:149], v[232:233], v[176:177], v[148:149]
	v_pk_fma_f32 v[150:151], v[234:235], v[178:179], v[150:151]
	v_pk_fma_f32 v[148:149], v[180:181], v[94:95], v[148:149] op_sel:[0,1,0] op_sel_hi:[1,1,1]
	v_pk_fma_f32 v[150:151], v[182:183], v[94:95], v[150:151] op_sel:[0,1,0] op_sel_hi:[1,1,1]
	v_pk_add_f32 v[188:189], v[188:189], 1.0 op_sel_hi:[1,0]
	v_pk_add_f32 v[190:191], v[190:191], 1.0 op_sel_hi:[1,0]
	v_rcp_f32_e32 v188, v188
	v_rcp_f32_e32 v189, v189
	v_rcp_f32_e32 v190, v190
	v_rcp_f32_e32 v191, v191
	v_pk_mul_f32 v[188:189], v[188:189], v[184:185]
	v_pk_mul_f32 v[190:191], v[190:191], v[186:187]
	v_pk_mul_f32 v[152:153], v[148:149], v[188:189]
	v_pk_mul_f32 v[154:155], v[150:151], v[190:191]
	v_cvt_pk_bf16_f32 v176, v152, v1
	ds_write_b16 v129, v176
	v_cvt_pk_bf16_f32 v177, v153, v1
	ds_write_b16 v129, v177 offset:144
	v_cvt_pk_bf16_f32 v178, v154, v1
	ds_write_b16 v129, v178 offset:288
	v_cvt_pk_bf16_f32 v179, v155, v1
	ds_write_b16 v129, v179 offset:432
	v_lshlrev_b32_e32 v184, 16, v250
	v_and_b32_e32 v185, 0xffff0000, v250
	v_lshlrev_b32_e32 v186, 16, v251
	v_and_b32_e32 v187, 0xffff0000, v251
	s_waitcnt lgkmcnt(7)
	v_lshlrev_b32_e32 v180, 16, v172
	s_waitcnt lgkmcnt(6)
	v_lshlrev_b32_e32 v181, 16, v173
	s_waitcnt lgkmcnt(5)
	v_lshlrev_b32_e32 v182, 16, v215
	s_waitcnt lgkmcnt(4)
	v_lshlrev_b32_e32 v183, 16, v102
	v_mul_f32_e32 v188, 0xbfb8aa3b, v180
	v_mul_f32_e32 v189, 0xbfb8aa3b, v181
	v_mul_f32_e32 v190, 0xbfb8aa3b, v182
	v_mul_f32_e32 v191, 0xbfb8aa3b, v183
	v_exp_f32_e32 v188, v188
	v_exp_f32_e32 v189, v189
	v_exp_f32_e32 v190, v190
	v_exp_f32_e32 v191, v191
	v_pk_fma_f32 v[58:59], v[232:233], v[216:217], v[58:59]
	v_pk_fma_f32 v[60:61], v[234:235], v[218:219], v[60:61]
	v_pk_fma_f32 v[58:59], v[184:185], v[94:95], v[58:59] op_sel:[0,1,0] op_sel_hi:[1,1,1]
	v_pk_fma_f32 v[60:61], v[186:187], v[94:95], v[60:61] op_sel:[0,1,0] op_sel_hi:[1,1,1]
	v_pk_add_f32 v[188:189], v[188:189], 1.0 op_sel_hi:[1,0]
	v_pk_add_f32 v[190:191], v[190:191], 1.0 op_sel_hi:[1,0]
	v_rcp_f32_e32 v188, v188
	v_rcp_f32_e32 v189, v189
	v_rcp_f32_e32 v190, v190
	v_rcp_f32_e32 v191, v191
	v_pk_mul_f32 v[188:189], v[188:189], v[180:181]
	v_pk_mul_f32 v[190:191], v[190:191], v[182:183]
	v_pk_mul_f32 v[62:63], v[58:59], v[188:189]
	v_pk_mul_f32 v[64:65], v[60:61], v[190:191]
	v_cvt_pk_bf16_f32 v220, v62, v1
	ds_write_b16 v132, v220
	v_cvt_pk_bf16_f32 v221, v63, v1
	ds_write_b16 v132, v221 offset:144
	v_cvt_pk_bf16_f32 v222, v64, v1
	ds_write_b16 v132, v222 offset:288
	v_cvt_pk_bf16_f32 v223, v65, v1
	ds_write_b16 v132, v223 offset:432
	v_pk_mul_f32 v[156:157], v[62:63], v[62:63]
	v_pk_mul_f32 v[158:159], v[64:65], v[64:65]
	v_pk_fma_f32 v[156:157], v[152:153], v[152:153], v[156:157]
	v_pk_fma_f32 v[158:159], v[154:155], v[154:155], v[158:159]
	s_nop 0
	v_add_f32_dpp v156, v156, v156 quad_perm:[1,0,3,2] row_mask:0xf bank_mask:0xf bound_ctrl:1
	v_add_f32_dpp v157, v157, v157 quad_perm:[1,0,3,2] row_mask:0xf bank_mask:0xf bound_ctrl:1
	v_add_f32_dpp v158, v158, v158 quad_perm:[1,0,3,2] row_mask:0xf bank_mask:0xf bound_ctrl:1
	v_add_f32_dpp v159, v159, v159 quad_perm:[1,0,3,2] row_mask:0xf bank_mask:0xf bound_ctrl:1
	v_add_f32_dpp v156, v156, v156 quad_perm:[2,3,0,1] row_mask:0xf bank_mask:0xf bound_ctrl:1
	v_add_f32_dpp v157, v157, v157 quad_perm:[2,3,0,1] row_mask:0xf bank_mask:0xf bound_ctrl:1
	v_add_f32_dpp v158, v158, v158 quad_perm:[2,3,0,1] row_mask:0xf bank_mask:0xf bound_ctrl:1
	v_add_f32_dpp v159, v159, v159 quad_perm:[2,3,0,1] row_mask:0xf bank_mask:0xf bound_ctrl:1
	v_add_f32_dpp v156, v156, v156 row_half_mirror row_mask:0xf bank_mask:0xf bound_ctrl:1
	v_add_f32_dpp v157, v157, v157 row_half_mirror row_mask:0xf bank_mask:0xf bound_ctrl:1
	v_add_f32_dpp v158, v158, v158 row_half_mirror row_mask:0xf bank_mask:0xf bound_ctrl:1
	v_add_f32_dpp v159, v159, v159 row_half_mirror row_mask:0xf bank_mask:0xf bound_ctrl:1
	v_mov_b32_dpp v160, v156 row_mirror row_mask:0xf bank_mask:0xf bound_ctrl:1
	v_mov_b32_dpp v161, v157 row_mirror row_mask:0xf bank_mask:0xf bound_ctrl:1
	v_mov_b32_dpp v162, v158 row_mirror row_mask:0xf bank_mask:0xf bound_ctrl:1
	v_mov_b32_dpp v163, v159 row_mirror row_mask:0xf bank_mask:0xf bound_ctrl:1
	s_and_saveexec_b64 s[20:21], s[6:7]
	v_add_f32_e32 v156, v156, v160
	v_add_f32_e32 v157, v157, v161
	v_add_f32_e32 v158, v158, v162
	v_add_f32_e32 v159, v159, v163
	ds_write_b32 v133, v156
	ds_write_b32 v134, v157
	ds_write_b32 v135, v158
	ds_write_b32 v136, v159
	s_or_b64 exec, exec, s[20:21]
	s_waitcnt lgkmcnt(0)
	s_barrier
	s_and_saveexec_b64 s[20:21], s[38:39]
	s_cbranch_execz .LBB0_560
	s_nop 1
	ds_read_b64 v[58:59], v145
	v_add_u32_e32 v60, s15, v116
	s_waitcnt lgkmcnt(0)
	v_add_f32_e32 v58, v58, v59
	ds_write_b32 v60, v58
	s_branch .LBB0_560
